# slot pass also takes the layer-0 FFN down weights and the attention out-projection weights
# speedup vs baseline: 1.0156x; 1.0006x over previous
; template <class F> DI void tr_items(const F& f, int Kdst, int Nrows, bf16_t* WT, LAS float* scr, int gw, int NGW, int lane, int& cum) {
;     const int nblk = Nrows / 32, nitems = (Kdst / 64) * nblk;
;     int first = (gw - cum) % NGW; if (first < 0) first += NGW; cum = (cum + nitems) % NGW;
;     for (int item = first; item < nitems; item += NGW) {
; DI void phase_prologue(int wv, const ArgP a, LAS unsigned char* lds, int parts) {
;     ...
;     { FWP f{a.in(15), 1024}; tr_items(f, 1024, 1024, (bf16_t*)(ws + O_WO1T), scr, gw, NGW, lane, cum); }
.LBB0_286:
	s_or_b64 exec, exec, s[0:1]
	s_mul_i32 s19, s19, s15
	s_sub_i32 s1, s18, s19
	s_ashr_i32 s0, s20, 31
	s_sub_i32 s4, s1, s15
	s_cmp_ge_u32 s1, s15
	s_cselect_b32 s1, s4, s1
	s_sub_i32 s4, s1, s15
	s_cmp_ge_u32 s1, s15
	s_cselect_b32 s1, s4, s1
	s_xor_b32 s1, s1, s0
	s_sub_i32 s8, s1, s0
	v_subrev_u32_e32 v2, s8, v0
	v_sub_u32_e32 v4, 0, v2
	v_ashrrev_i32_e32 v3, 31, v2
	v_max_i32_e32 v2, v2, v4
	v_mul_hi_u32 v4, v2, s25
	v_mul_lo_u32 v4, v4, s15
	v_sub_u32_e32 v2, v2, v4
	v_subrev_u32_e32 v4, s15, v2
	v_cmp_le_u32_e32 vcc, s15, v2
	s_movk_i32 s0, 0x1ff
	s_nop 0
	v_cndmask_b32_e32 v2, v2, v4, vcc
	v_subrev_u32_e32 v4, s15, v2
	v_cmp_le_u32_e32 vcc, s15, v2
	s_nop 1
	v_cndmask_b32_e32 v2, v2, v4, vcc
	v_xor_b32_e32 v2, v2, v3
	v_sub_u32_e32 v2, v2, v3
	v_ashrrev_i32_e32 v3, 31, v2
	v_and_b32_e32 v3, s14, v3
	v_add_u32_e32 v13, v3, v2
	v_cmp_lt_i32_e32 vcc, s0, v13
	s_or_b64 vcc, vcc, s[94:95]
	s_and_saveexec_b64 s[0:1], vcc
	s_xor_b64 s[0:1], exec, s[0:1]
	s_cbranch_execz .LBB0_288
	v_lshrrev_b32_e32 v17, 5, v16
	v_lshrrev_b32_e32 v19, 3, v16
	v_and_b32_e32 v2, 56, v21
	v_and_b32_e32 v18, 31, v14
	v_mul_u32_u24_e32 v8, 0x84, v2
	v_mov_b32_e32 v3, 0
	v_mul_u32_u24_e32 v9, 0x84, v17
	v_or_b32_e32 v10, 8, v19
	v_or_b32_e32 v11, 16, v19
	v_or_b32_e32 v12, 24, v19

; template <class F> DI void tr_items(const F& f, int Kdst, int Nrows, bf16_t* WT, LAS float* scr, int gw, int NGW, int lane, int& cum) {
;     const int nblk = Nrows / 32, nitems = (Kdst / 64) * nblk;
;     int first = (gw - cum) % NGW; if (first < 0) first += NGW; cum = (cum + nitems) % NGW;
;     for (int item = first; item < nitems; item += NGW) {
; DI void phase_prologue(int wv, const ArgP a, LAS unsigned char* lds, int parts) {
;     ...
;         { FWP f{a.in(26) + (size_t)l * 2816 * 1024, 1024}; tr_items(f, 2816, 1024, (bf16_t*)(ws + (l ? O_WDNT1 : O_WDNT0)), scr, gw, NGW, lane, cum); }
.LBB0_297:
	s_or_b64 exec, exec, s[16:17]
	s_add_i32 s0, s42, 0xb00
	s_ashr_i32 s16, s0, 31
	s_abs_i32 s0, s0
	s_mul_hi_u32 s17, s0, s25
	s_mul_i32 s17, s17, s15
	s_sub_i32 s0, s0, s17
	s_xor_b64 s[4:5], s[6:7], -1
	s_sub_i32 s17, s0, s15
	s_cmp_ge_u32 s0, s15
	s_cselect_b32 s0, s17, s0
	s_sub_i32 s17, s0, s15
	s_cmp_ge_u32 s0, s15
	s_cselect_b32 s0, s17, s0
	s_xor_b32 s0, s0, s16
	s_sub_i32 s20, s0, s16
	v_subrev_u32_e32 v4, s20, v0
	v_sub_u32_e32 v6, 0, v4
	v_ashrrev_i32_e32 v5, 31, v4
	v_max_i32_e32 v4, v4, v6
	v_mul_hi_u32 v6, v4, s25
	v_mul_lo_u32 v6, v6, s15
	v_sub_u32_e32 v4, v4, v6
	v_subrev_u32_e32 v6, s15, v4
	v_cmp_le_u32_e32 vcc, s15, v4
	s_nop 1
	v_cndmask_b32_e32 v4, v4, v6, vcc
	v_subrev_u32_e32 v6, s15, v4
	v_cmp_le_u32_e32 vcc, s15, v4
	s_nop 1
	v_cndmask_b32_e32 v4, v4, v6, vcc
	v_xor_b32_e32 v4, v4, v5
	v_sub_u32_e32 v4, v4, v5
	v_ashrrev_i32_e32 v5, 31, v4
	v_and_b32_e32 v5, s14, v5
	v_add_u32_e32 v8, v5, v4
	v_cmp_gt_i32_e32 vcc, s37, v8
	s_and_b64 vcc, vcc, s[96:97]
	s_and_saveexec_b64 s[16:17], vcc
	s_cbranch_execz .LBB0_293
	s_load_dwordx2 s[18:19], s[2:3], 0xd0
	s_mul_i32 s0, s43, 0xb00000
	v_mul_lo_u32 v34, v8, s39
	s_mul_i32 s21, s14, 0x16000
	v_lshl_add_u32 v35, v8, 5, v18
	s_waitcnt lgkmcnt(0)
	s_add_u32 s18, s18, s0
	s_addc_u32 s19, s19, 0
	s_and_b64 s[6:7], s[6:7], exec
	s_cselect_b32 s0, s38, 0xb00000
	v_lshl_add_u64 v[4:5], v[2:3], 0, s[0:1]
	s_mov_b64 s[6:7], 0
